# attention units re-indexed: the 8 q blocks of one (b,h) run in the same round on 8 workgroups of one XCD (K/V tiles shared in L2); bijective remap, balanced 72 tiles per WG
# speedup vs baseline: 1.0036x; 1.0036x over previous
; __device__ __forceinline__ void attn_phase(const Args& a, LAS unsigned char* lds, int G, int wv) {
;     ...
;     for (int L = blockIdx.x; L < 1024; L += G) {
;         const int i = L >> 8, c = L & 255, bh = c >> 1, s = c & 1;
;         const int qb = (i == 0) ? (s ? 6 : 7) : (i == 1) ? (s ? 1 : 0) : (i == 2) ? (s ? 4 : 5) : (s ? 3 : 2);
;         attn_unit(bh, qb, Q, KN, KPE, VT, COS, SIN, O, lds, wv);
.LBB0_561:
	s_and_b32 s93, s48, 0xff
	s_lshr_b32 s94, s48, 8
	s_and_b32 s95, s93, 7
	s_lshr_b32 s93, s93, 3
	s_lshr_b32 s96, s93, 3
	s_and_b32 s93, s93, 7
	s_lshl_b32 s95, s95, 4
	s_lshl_b32 s96, s96, 2
	s_add_i32 s95, s95, s96
	s_add_i32 s95, s95, s94
	s_lshl_b32 s95, s95, 1
	s_and_b32 s96, s93, 1
	s_or_b32 s95, s95, s96
	s_lshr_b32 s93, s93, 1
	s_xor_b32 s93, s93, s94
	s_lshl_b32 s93, s93, 8
	s_or_b32 s93, s93, s95
	s_and_b32 s2, s93, 1
	s_cmpk_gt_u32 s93, 0xff
	s_mov_b64 s[6:7], -1
	s_cbranch_scc0 .LBB0_571
	s_ashr_i32 s18, s93, 8
	s_cmp_lt_i32 s18, 2
	s_cbranch_scc1 .LBB0_566
	s_cmp_eq_u32 s18, 2
	s_cbranch_scc0 .LBB0_565
	s_xor_b32 s50, s2, 5
	s_mov_b64 s[6:7], 0

; __device__ __forceinline__ void attn_unit(int bh, int qb, const bf16_t* Q, const bf16_t* KN, const bf16_t* KPE, const bf16_t* VT, const float* COS, const float* SIN, bf16_t* O, LAS unsigned char* lds, int wv) {
;     ...
;     const int b = bh >> 4, h = bh & 15, q0 = qb * 256;
;     const size_t rowbase = (size_t)b * 2048;
;     const int qrow = q0 + 32 * wid + r32;
;     const unsigned lds0 = (unsigned)(uintptr_t)lds;
;     const bf16_t* csrc[6]; int cstep[6]; unsigned cdst[6];
; #pragma unroll
;     for (int i = 0; i < 6; ++i) { int id = wid + 8 * i; if (id > 44) id = 44;
;         if (id < 25) { const int c = id * 1024 + 16 * lane, row = c / AK_PITCH, col = c % AK_PITCH;
;             if (col < 256) { csrc[i] = KN + (rowbase + row) * 2048 + h * 128 + (col >> 1); cstep[i] = 64 * 2048; }
;             else if (col < 384) { csrc[i] = KPE + (rowbase + row) * 64 + ((col - 256) >> 1); cstep[i] = 64 * 64; }
;             else { csrc[i] = KN + (rowbase + row) * 2048 + h * 128; cstep[i] = 64 * 2048; }
;             cdst[i] = (unsigned)(id * 1024); }
;         else { const int c = (id - 25) * 1024 + 16 * lane, row = c / AV_PITCH, col = c % AV_PITCH;
;             csrc[i] = VT + (rowbase + row) * 2048 + h * 128 + (col < 256 ? (col >> 1) : 0); cstep[i] = 64 * 2048;
;             cdst[i] = (unsigned)(3 * AK_BYTES + (id - 25) * 1024); } }
.LBB0_573:
	v_mbcnt_lo_u32_b32 v188, -1, 0
	v_mbcnt_hi_u32_b32 v188, -1, v188
	s_bfe_u32 s53, s93, 0x40001
	v_or_b32_e32 v0, s90, v188
	s_lshl_b32 s6, s53, 8
	v_readfirstlane_b32 s2, v0
	s_ashr_i32 s49, s2, 6
	s_lshl_b32 s2, s93, 6
	s_and_b32 s2, s2, 0x3800
	s_add_u32 s24, s38, s6
	s_addc_u32 s25, s39, 0
	s_add_u32 s22, s36, s6
	s_addc_u32 s23, s37, 0
	s_min_i32 s16, s49, 44
	v_and_b32_e32 v189, 63, v188
	s_cmp_lt_i32 s49, 25
	v_lshlrev_b32_e32 v4, 4, v189
	s_cselect_b64 s[6:7], -1, 0
	s_lshl_b32 s20, s16, 10
	v_or_b32_e32 v5, 0xffff9c00, v4
	s_cmp_gt_i32 s49, 24
	s_mov_b64 s[16:17], -1
	s_cbranch_scc0 .LBB0_575
	v_add_u32_e32 v0, s20, v5
	v_mul_hi_u32 v2, v0, s35
	v_lshrrev_b32_e32 v2, 8, v2
	v_mul_u32_u24_e32 v3, 0x140, v2
	v_sub_u32_e32 v6, v0, v3
	v_add_u32_e32 v0, s2, v2
	v_lshlrev_b64 v[2:3], 12, v[0:1]
	v_lshrrev_b32_e32 v0, 1, v6
	v_cmp_gt_u32_e32 vcc, s42, v6
	v_lshl_add_u64 v[2:3], s[24:25], 0, v[2:3]
	s_add_i32 s54, s20, 0xc800
	v_cndmask_b32_e32 v0, 0, v0, vcc
	v_lshlrev_b32_e32 v0, 1, v0
	v_lshl_add_u64 v[10:11], v[2:3], 0, v[0:1]
	s_mov_b64 s[16:17], 0
